# v075 plus hand-scheduled SwiGLU epilogue: same instructions and math, software-pipelined across the 16 accumulator quads, no s_nop fillers, addresses computed up front
# baseline (speedup 1.0000x reference)
.LBB0_1568:
	v_lshl_add_u32 v158, s16, 7, v161
	v_ashrrev_i32_e32 v158, 6, v158
	v_ashrrev_i32_e32 v159, 31, v158
	v_mov_b32_e32 v163, 0x58
	v_mad_i64_i32 v[158:159], s[14:15], s14, v163, v[158:159]
	v_pk_mul_f32 v[126:127], v[122:123], v[126:127]
	v_pk_mul_f32 v[128:129], v[124:125], v[128:129]
	v_lshlrev_b64 v[158:159], 15, v[158:159]
	v_pk_mul_f32 v[118:119], v[114:115], v[118:119]
	v_pk_mul_f32 v[120:121], v[116:117], v[120:121]
	v_lshl_add_u64 v[158:159], v[152:153], 0, v[158:159]
	v_lshl_add_u64 v[164:165], v[158:159], 0, v[136:137]
	v_lshl_add_u64 v[166:167], v[158:159], 0, v[138:139]
	v_lshl_add_u64 v[168:169], v[158:159], 0, v[140:141]
	v_lshl_add_u64 v[170:171], v[158:159], 0, v[142:143]
	v_lshl_add_u64 v[172:173], v[158:159], 0, v[144:145]
	v_lshl_add_u64 v[174:175], v[158:159], 0, v[146:147]
	v_lshl_add_u64 v[176:177], v[158:159], 0, v[148:149]
	v_lshl_add_u64 v[178:179], v[158:159], 0, v[150:151]
	v_exp_f32_e32 v122, v122
	v_exp_f32_e32 v123, v123
	v_exp_f32_e32 v124, v124
	v_exp_f32_e32 v125, v125
	v_pk_mul_f32 v[110:111], v[106:107], v[110:111]
	v_pk_mul_f32 v[112:113], v[108:109], v[112:113]
	v_add_f32_e32 v122, 1.0, v122
	v_add_f32_e32 v123, 1.0, v123
	v_add_f32_e32 v124, 1.0, v124
	v_add_f32_e32 v125, 1.0, v125
	v_exp_f32_e32 v114, v114
	v_exp_f32_e32 v115, v115
	v_exp_f32_e32 v116, v116
	v_exp_f32_e32 v117, v117
	v_rcp_f32_e32 v122, v122
	v_rcp_f32_e32 v123, v123
	v_rcp_f32_e32 v124, v124
	v_rcp_f32_e32 v125, v125
	v_pk_mul_f32 v[102:103], v[98:99], v[102:103]
	v_pk_mul_f32 v[104:105], v[100:101], v[104:105]
	v_add_f32_e32 v114, 1.0, v114
	v_add_f32_e32 v115, 1.0, v115
	v_add_f32_e32 v116, 1.0, v116
	v_add_f32_e32 v117, 1.0, v117
	v_pk_mul_f32 v[122:123], v[122:123], v[126:127]
	v_pk_mul_f32 v[124:125], v[124:125], v[128:129]
	v_exp_f32_e32 v106, v106
	v_exp_f32_e32 v107, v107
	v_exp_f32_e32 v108, v108
	v_exp_f32_e32 v109, v109
	v_rcp_f32_e32 v114, v114
	v_rcp_f32_e32 v115, v115
	v_rcp_f32_e32 v116, v116
	v_rcp_f32_e32 v117, v117
	v_pk_mul_f32 v[94:95], v[90:91], v[94:95]
	v_pk_mul_f32 v[96:97], v[92:93], v[96:97]
	v_add_f32_e32 v106, 1.0, v106
	v_add_f32_e32 v107, 1.0, v107
	v_add_f32_e32 v108, 1.0, v108
	v_add_f32_e32 v109, 1.0, v109
	v_pk_mul_f32 v[114:115], v[114:115], v[118:119]
	v_pk_mul_f32 v[116:117], v[116:117], v[120:121]
	v_cvt_pk_bf16_f32 v122, v122, v123
	v_cvt_pk_bf16_f32 v123, v124, v125
	v_exp_f32_e32 v98, v98
	v_exp_f32_e32 v99, v99
	v_exp_f32_e32 v100, v100
	v_exp_f32_e32 v101, v101
	v_rcp_f32_e32 v106, v106
	v_rcp_f32_e32 v107, v107
	v_rcp_f32_e32 v108, v108
	v_rcp_f32_e32 v109, v109
	v_pk_mul_f32 v[86:87], v[82:83], v[86:87]
	v_pk_mul_f32 v[88:89], v[84:85], v[88:89]
	v_add_f32_e32 v98, 1.0, v98
	v_add_f32_e32 v99, 1.0, v99
	v_add_f32_e32 v100, 1.0, v100
	v_add_f32_e32 v101, 1.0, v101
	v_pk_mul_f32 v[106:107], v[106:107], v[110:111]
	v_pk_mul_f32 v[108:109], v[108:109], v[112:113]
	v_cvt_pk_bf16_f32 v124, v114, v115
	v_cvt_pk_bf16_f32 v125, v116, v117
	global_store_dwordx4 v[164:165], v[122:125], off
	v_exp_f32_e32 v90, v90
	v_exp_f32_e32 v91, v91
	v_exp_f32_e32 v92, v92
	v_exp_f32_e32 v93, v93
	v_rcp_f32_e32 v98, v98
	v_rcp_f32_e32 v99, v99
	v_rcp_f32_e32 v100, v100
	v_rcp_f32_e32 v101, v101
	v_pk_mul_f32 v[78:79], v[74:75], v[78:79]
	v_pk_mul_f32 v[80:81], v[76:77], v[80:81]
	v_add_f32_e32 v90, 1.0, v90
	v_add_f32_e32 v91, 1.0, v91
	v_add_f32_e32 v92, 1.0, v92
	v_add_f32_e32 v93, 1.0, v93
	v_pk_mul_f32 v[98:99], v[98:99], v[102:103]
	v_pk_mul_f32 v[100:101], v[100:101], v[104:105]
	v_cvt_pk_bf16_f32 v106, v106, v107
	v_cvt_pk_bf16_f32 v107, v108, v109
	v_exp_f32_e32 v82, v82
	v_exp_f32_e32 v83, v83
	v_exp_f32_e32 v84, v84
	v_exp_f32_e32 v85, v85
	v_rcp_f32_e32 v90, v90
	v_rcp_f32_e32 v91, v91
	v_rcp_f32_e32 v92, v92
	v_rcp_f32_e32 v93, v93
	v_pk_mul_f32 v[70:71], v[66:67], v[70:71]
	v_pk_mul_f32 v[72:73], v[68:69], v[72:73]
	v_add_f32_e32 v82, 1.0, v82
	v_add_f32_e32 v83, 1.0, v83
	v_add_f32_e32 v84, 1.0, v84
	v_add_f32_e32 v85, 1.0, v85
	v_pk_mul_f32 v[90:91], v[90:91], v[94:95]
	v_pk_mul_f32 v[92:93], v[92:93], v[96:97]
	v_cvt_pk_bf16_f32 v108, v98, v99
	v_cvt_pk_bf16_f32 v109, v100, v101
	global_store_dwordx4 v[166:167], v[106:109], off
	v_exp_f32_e32 v74, v74
	v_exp_f32_e32 v75, v75
	v_exp_f32_e32 v76, v76
	v_exp_f32_e32 v77, v77
	v_rcp_f32_e32 v82, v82
	v_rcp_f32_e32 v83, v83
	v_rcp_f32_e32 v84, v84
	v_rcp_f32_e32 v85, v85
	v_pk_mul_f32 v[62:63], v[58:59], v[62:63]
	v_pk_mul_f32 v[64:65], v[60:61], v[64:65]
	v_add_f32_e32 v74, 1.0, v74
	v_add_f32_e32 v75, 1.0, v75
	v_add_f32_e32 v76, 1.0, v76
	v_add_f32_e32 v77, 1.0, v77
	v_pk_mul_f32 v[82:83], v[82:83], v[86:87]
	v_pk_mul_f32 v[84:85], v[84:85], v[88:89]
	v_cvt_pk_bf16_f32 v90, v90, v91
	v_cvt_pk_bf16_f32 v91, v92, v93
	v_exp_f32_e32 v66, v66
	v_exp_f32_e32 v67, v67
	v_exp_f32_e32 v68, v68
	v_exp_f32_e32 v69, v69
	v_rcp_f32_e32 v74, v74
	v_rcp_f32_e32 v75, v75
	v_rcp_f32_e32 v76, v76
	v_rcp_f32_e32 v77, v77
	v_pk_mul_f32 v[54:55], v[50:51], v[54:55]
	v_pk_mul_f32 v[56:57], v[52:53], v[56:57]
	v_add_f32_e32 v66, 1.0, v66
	v_add_f32_e32 v67, 1.0, v67
	v_add_f32_e32 v68, 1.0, v68
	v_add_f32_e32 v69, 1.0, v69
	v_pk_mul_f32 v[74:75], v[74:75], v[78:79]
	v_pk_mul_f32 v[76:77], v[76:77], v[80:81]
	v_cvt_pk_bf16_f32 v92, v82, v83
	v_cvt_pk_bf16_f32 v93, v84, v85
	global_store_dwordx4 v[168:169], v[90:93], off
	v_exp_f32_e32 v58, v58
	v_exp_f32_e32 v59, v59
	v_exp_f32_e32 v60, v60
	v_exp_f32_e32 v61, v61
	v_rcp_f32_e32 v66, v66
	v_rcp_f32_e32 v67, v67
	v_rcp_f32_e32 v68, v68
	v_rcp_f32_e32 v69, v69
	v_pk_mul_f32 v[46:47], v[42:43], v[46:47]
	v_pk_mul_f32 v[48:49], v[44:45], v[48:49]
	v_add_f32_e32 v58, 1.0, v58
	v_add_f32_e32 v59, 1.0, v59
	v_add_f32_e32 v60, 1.0, v60
	v_add_f32_e32 v61, 1.0, v61
	v_pk_mul_f32 v[66:67], v[66:67], v[70:71]
	v_pk_mul_f32 v[68:69], v[68:69], v[72:73]
	v_cvt_pk_bf16_f32 v74, v74, v75
	v_cvt_pk_bf16_f32 v75, v76, v77
	v_exp_f32_e32 v50, v50
	v_exp_f32_e32 v51, v51
	v_exp_f32_e32 v52, v52
	v_exp_f32_e32 v53, v53
	v_rcp_f32_e32 v58, v58
	v_rcp_f32_e32 v59, v59
	v_rcp_f32_e32 v60, v60
	v_rcp_f32_e32 v61, v61
	v_pk_mul_f32 v[38:39], v[34:35], v[38:39]
	v_pk_mul_f32 v[40:41], v[36:37], v[40:41]
	v_add_f32_e32 v50, 1.0, v50
	v_add_f32_e32 v51, 1.0, v51
	v_add_f32_e32 v52, 1.0, v52
	v_add_f32_e32 v53, 1.0, v53
	v_pk_mul_f32 v[58:59], v[58:59], v[62:63]
	v_pk_mul_f32 v[60:61], v[60:61], v[64:65]
	v_cvt_pk_bf16_f32 v76, v66, v67
	v_cvt_pk_bf16_f32 v77, v68, v69
	global_store_dwordx4 v[170:171], v[74:77], off
	v_exp_f32_e32 v42, v42
	v_exp_f32_e32 v43, v43
	v_exp_f32_e32 v44, v44
	v_exp_f32_e32 v45, v45
	v_rcp_f32_e32 v50, v50
	v_rcp_f32_e32 v51, v51
	v_rcp_f32_e32 v52, v52
	v_rcp_f32_e32 v53, v53
	v_pk_mul_f32 v[30:31], v[26:27], v[30:31]
	v_pk_mul_f32 v[32:33], v[28:29], v[32:33]
	v_add_f32_e32 v42, 1.0, v42
	v_add_f32_e32 v43, 1.0, v43
	v_add_f32_e32 v44, 1.0, v44
	v_add_f32_e32 v45, 1.0, v45
	v_pk_mul_f32 v[50:51], v[50:51], v[54:55]
	v_pk_mul_f32 v[52:53], v[52:53], v[56:57]
	v_cvt_pk_bf16_f32 v58, v58, v59
	v_cvt_pk_bf16_f32 v59, v60, v61
	v_exp_f32_e32 v34, v34
	v_exp_f32_e32 v35, v35
	v_exp_f32_e32 v36, v36
	v_exp_f32_e32 v37, v37
	v_rcp_f32_e32 v42, v42
	v_rcp_f32_e32 v43, v43
	v_rcp_f32_e32 v44, v44
	v_rcp_f32_e32 v45, v45
	v_pk_mul_f32 v[22:23], v[18:19], v[22:23]
	v_pk_mul_f32 v[24:25], v[20:21], v[24:25]
	v_add_f32_e32 v34, 1.0, v34
	v_add_f32_e32 v35, 1.0, v35
	v_add_f32_e32 v36, 1.0, v36
	v_add_f32_e32 v37, 1.0, v37
	v_pk_mul_f32 v[42:43], v[42:43], v[46:47]
	v_pk_mul_f32 v[44:45], v[44:45], v[48:49]
	v_cvt_pk_bf16_f32 v60, v50, v51
	v_cvt_pk_bf16_f32 v61, v52, v53
	global_store_dwordx4 v[172:173], v[58:61], off
	v_exp_f32_e32 v26, v26
	v_exp_f32_e32 v27, v27
	v_exp_f32_e32 v28, v28
	v_exp_f32_e32 v29, v29
	v_rcp_f32_e32 v34, v34
	v_rcp_f32_e32 v35, v35
	v_rcp_f32_e32 v36, v36
	v_rcp_f32_e32 v37, v37
	v_pk_mul_f32 v[14:15], v[10:11], v[14:15]
	v_pk_mul_f32 v[16:17], v[12:13], v[16:17]
	v_add_f32_e32 v26, 1.0, v26
	v_add_f32_e32 v27, 1.0, v27
	v_add_f32_e32 v28, 1.0, v28
	v_add_f32_e32 v29, 1.0, v29
	v_pk_mul_f32 v[34:35], v[34:35], v[38:39]
	v_pk_mul_f32 v[36:37], v[36:37], v[40:41]
	v_cvt_pk_bf16_f32 v42, v42, v43
	v_cvt_pk_bf16_f32 v43, v44, v45
	v_exp_f32_e32 v18, v18
	v_exp_f32_e32 v19, v19
	v_exp_f32_e32 v20, v20
	v_exp_f32_e32 v21, v21
	v_rcp_f32_e32 v26, v26
	v_rcp_f32_e32 v27, v27
	v_rcp_f32_e32 v28, v28
	v_rcp_f32_e32 v29, v29
	v_pk_mul_f32 v[6:7], v[2:3], v[6:7]
	v_pk_mul_f32 v[8:9], v[4:5], v[8:9]
	v_add_f32_e32 v18, 1.0, v18
	v_add_f32_e32 v19, 1.0, v19
	v_add_f32_e32 v20, 1.0, v20
	v_add_f32_e32 v21, 1.0, v21
	v_pk_mul_f32 v[26:27], v[26:27], v[30:31]
	v_pk_mul_f32 v[28:29], v[28:29], v[32:33]
	v_cvt_pk_bf16_f32 v44, v34, v35
	v_cvt_pk_bf16_f32 v45, v36, v37
	global_store_dwordx4 v[174:175], v[42:45], off
	v_exp_f32_e32 v10, v10
	v_exp_f32_e32 v11, v11
	v_exp_f32_e32 v12, v12
	v_exp_f32_e32 v13, v13
	v_rcp_f32_e32 v18, v18
	v_rcp_f32_e32 v19, v19
	v_rcp_f32_e32 v20, v20
	v_rcp_f32_e32 v21, v21
	v_add_f32_e32 v10, 1.0, v10
	v_add_f32_e32 v11, 1.0, v11
	v_add_f32_e32 v12, 1.0, v12
	v_add_f32_e32 v13, 1.0, v13
	v_pk_mul_f32 v[18:19], v[18:19], v[22:23]
	v_pk_mul_f32 v[20:21], v[20:21], v[24:25]
	v_cvt_pk_bf16_f32 v26, v26, v27
	v_cvt_pk_bf16_f32 v27, v28, v29
	v_exp_f32_e32 v2, v2
	v_exp_f32_e32 v3, v3
	v_exp_f32_e32 v4, v4
	v_exp_f32_e32 v5, v5
	v_rcp_f32_e32 v10, v10
	v_rcp_f32_e32 v11, v11
	v_rcp_f32_e32 v12, v12
	v_rcp_f32_e32 v13, v13
	v_add_f32_e32 v2, 1.0, v2
	v_add_f32_e32 v3, 1.0, v3
	v_add_f32_e32 v4, 1.0, v4
	v_add_f32_e32 v5, 1.0, v5
	v_pk_mul_f32 v[10:11], v[10:11], v[14:15]
	v_pk_mul_f32 v[12:13], v[12:13], v[16:17]
	v_cvt_pk_bf16_f32 v28, v18, v19
	v_cvt_pk_bf16_f32 v29, v20, v21
	global_store_dwordx4 v[176:177], v[26:29], off
	v_rcp_f32_e32 v2, v2
	v_rcp_f32_e32 v3, v3
	v_rcp_f32_e32 v4, v4
	v_rcp_f32_e32 v5, v5
	v_pk_mul_f32 v[2:3], v[2:3], v[6:7]
	v_pk_mul_f32 v[4:5], v[4:5], v[8:9]
	v_cvt_pk_bf16_f32 v10, v10, v11
	v_cvt_pk_bf16_f32 v11, v12, v13
	v_cvt_pk_bf16_f32 v12, v2, v3
	v_cvt_pk_bf16_f32 v13, v4, v5
	global_store_dwordx4 v[178:179], v[10:13], off
	s_mov_b64 s[14:15], -1
	s_andn2_b64 vcc, exec, s[34:35]
	s_cbranch_vccnz .LBB0_1561
	s_andn2_b64 vcc, exec, s[0:1]
	s_cbranch_vccnz .LBB0_1560
	s_branch .LBB0_1560
